# phase-5 router loop: 18 closely spaced s_waitcnt lgkmcnt pairs merged into the earlier, stricter wait
# baseline (speedup 1.0000x reference)
; DI unsigned pk2(float a, float b) { fl2_t f = {a, b}; bf2_t r = __builtin_convertvector(f, bf2_t); return __builtin_bit_cast(unsigned, r); }
; #define HSUM(v) do { v += __shfl_xor(v, 16, 64); v += __shfl_xor(v, 8, 64); v += __shfl_xor(v, 4, 64); v += __shfl_xor(v, 2, 64); v += __shfl_xor(v, 1, 64); } while (0)
; DI void phase5(const Params& p, char* lds0) {
;     ...
;       for (int j = 0; j < 8; ++j) {
;         float4 v = nx[j];
;         hv[j * 4 + 0] = v.x; hv[j * 4 + 1] = v.y; hv[j * 4 + 2] = v.z; hv[j * 4 + 3] = v.w;
;         ss += v.x * v.x + v.y * v.y + v.z * v.z + v.w * v.w;
;       }
;       if (i + 1 < 8) {
;         const float* x1 = p.out + (size_t)(t + 2) * D;
; #pragma unroll
;         for (int j = 0; j < 8; ++j) nx[j] = *(const float4*)(x1 + j * 128 + l32 * 4);
;       }
;     ...
;       HSUM(ss);
;       const float rstd = rsqrtf(ss * (1.f / 1024.f) + 1e-6f);
; #pragma unroll
;       for (int j = 0; j < 8; ++j) {
;         const int c = j * 128 + l32 * 4;
;         hv[j * 4 + 0] = hv[j * 4 + 0] * rstd * csv[j].x + shv[j].x;
;         hv[j * 4 + 1] = hv[j * 4 + 1] * rstd * csv[j].y + shv[j].y;
;         hv[j * 4 + 2] = hv[j * 4 + 2] * rstd * csv[j].z + shv[j].z;
;         hv[j * 4 + 3] = hv[j * 4 + 3] * rstd * csv[j].w + shv[j].w;
;         u32x2 o; o[0] = pk2(hv[j * 4 + 0], hv[j * 4 + 1]); o[1] = pk2(hv[j * 4 + 2], hv[j * 4 + 3]);
;         *(u32x2*)(H + (size_t)t * D + c) = o;
;       }
;       float lg[4];
; #pragma unroll
;       for (int n = 0; n < 4; ++n) {
;         float a = 0.f;
; #pragma unroll
;         for (int j = 0; j < 8; ++j) {
;           float4 wv = *(const float4*)(wg + n * 1024 + j * 128 + l32 * 4);
;           a += hv[j * 4 + 0] * wv.x + hv[j * 4 + 1] * wv.y + hv[j * 4 + 2] * wv.z + hv[j * 4 + 3] * wv.w;
.LBB0_259:
	s_waitcnt vmcnt(16)
	v_pk_mul_f32 v[160:161], v[94:95], v[94:95]
	s_waitcnt vmcnt(15)
	v_pk_mul_f32 v[164:165], v[90:91], v[90:91]
	v_pk_mul_f32 v[162:163], v[96:97], v[96:97]
	v_pk_mul_f32 v[166:167], v[92:93], v[92:93]
	v_add_f32_e32 v159, v161, v160
	v_add_f32_e32 v160, v165, v164
	v_add_f32_e32 v159, v162, v159
	v_add_f32_e32 v160, v166, v160
	s_waitcnt vmcnt(14)
	v_pk_mul_f32 v[168:169], v[86:87], v[86:87]
	v_add_f32_e32 v159, v163, v159
	v_add_f32_e32 v160, v167, v160
	v_pk_mul_f32 v[170:171], v[88:89], v[88:89]
	v_add_f32_e32 v159, v160, v159
	v_add_f32_e32 v160, v169, v168
	v_add_f32_e32 v160, v170, v160
	s_waitcnt vmcnt(13)
	v_pk_mul_f32 v[172:173], v[78:79], v[78:79]
	v_add_f32_e32 v160, v171, v160
	v_pk_mul_f32 v[188:189], v[80:81], v[80:81]
	v_add_f32_e32 v159, v160, v159
	v_add_f32_e32 v160, v173, v172
	v_add_f32_e32 v160, v188, v160
	s_waitcnt vmcnt(12)
	v_pk_mul_f32 v[190:191], v[70:71], v[70:71]
	v_add_f32_e32 v160, v189, v160
	v_pk_mul_f32 v[192:193], v[72:73], v[72:73]
	v_add_f32_e32 v159, v160, v159
	v_add_f32_e32 v160, v191, v190
	v_add_f32_e32 v160, v192, v160
	s_waitcnt vmcnt(11)
	v_pk_mul_f32 v[194:195], v[82:83], v[82:83]
	v_add_f32_e32 v160, v193, v160
	v_pk_mul_f32 v[196:197], v[84:85], v[84:85]
	v_add_f32_e32 v159, v160, v159
	v_add_f32_e32 v160, v194, v195
	v_add_f32_e32 v160, v160, v196
	s_waitcnt vmcnt(10)
	v_pk_mul_f32 v[198:199], v[74:75], v[74:75]
	v_add_f32_e32 v160, v160, v197
	v_pk_mul_f32 v[200:201], v[76:77], v[76:77]
	v_add_f32_e32 v159, v160, v159
	v_add_f32_e32 v160, v198, v199
	v_add_f32_e32 v160, v160, v200
	s_waitcnt vmcnt(9)
	v_pk_mul_f32 v[202:203], v[66:67], v[66:67]
	v_add_f32_e32 v160, v160, v201
	v_pk_mul_f32 v[204:205], v[68:69], v[68:69]
	v_add_f32_e32 v159, v159, v160
	v_add_f32_e32 v160, v202, v203
	v_add_f32_e32 v160, v160, v204
	v_add_f32_e32 v160, v160, v205
	v_add_f32_e32 v159, v159, v160
	ds_bpermute_b32 v160, v176, v159
	s_waitcnt lgkmcnt(0)
	v_add_f32_e32 v159, v159, v160
	ds_bpermute_b32 v160, v177, v159
	s_waitcnt lgkmcnt(0)
	v_add_f32_e32 v159, v159, v160
	ds_bpermute_b32 v160, v178, v159
	s_waitcnt lgkmcnt(0)
	v_add_f32_e32 v159, v159, v160
	ds_bpermute_b32 v160, v179, v159
	s_waitcnt lgkmcnt(0)
	v_add_f32_e32 v159, v159, v160
	ds_bpermute_b32 v160, v180, v159
	s_waitcnt lgkmcnt(0)
	v_add_f32_e32 v159, v159, v160
	v_fmamk_f32 v159, v159, 0x3a800000, v182
	v_mul_f32_e32 v160, 0x4b800000, v159
	v_cmp_gt_f32_e32 vcc, s40, v159
	s_nop 1
	v_cndmask_b32_e32 v159, v159, v160, vcc
	v_rsq_f32_e32 v159, v159
	s_nop 0
	v_mul_f32_e32 v160, 0x45800000, v159
	v_cndmask_b32_e32 v168, v159, v160, vcc
	v_pk_mul_f32 v[94:95], v[94:95], v[168:169] op_sel_hi:[1,0]
	v_ashrrev_i32_e32 v159, 31, v158
	v_pk_fma_f32 v[160:161], v[126:127], v[94:95], v[2:3]
	v_pk_mul_f32 v[94:95], v[96:97], v[168:169] op_sel_hi:[1,0]
	v_lshlrev_b64 v[164:165], 11, v[158:159]
	v_pk_fma_f32 v[162:163], v[128:129], v[94:95], v[4:5]
	v_pk_mul_f32 v[90:91], v[90:91], v[168:169] op_sel_hi:[1,0]
	v_cvt_pk_bf16_f32 v94, v160, v161
	v_cvt_pk_bf16_f32 v95, v162, v163
	v_lshl_add_u64 v[166:167], v[110:111], 0, v[164:165]
	v_pk_fma_f32 v[164:165], v[130:131], v[90:91], v[6:7]
	v_pk_mul_f32 v[90:91], v[92:93], v[168:169] op_sel_hi:[1,0]
	global_store_dwordx2 v[166:167], v[94:95], off
	v_pk_fma_f32 v[94:95], v[132:133], v[90:91], v[8:9]
	v_cvt_pk_bf16_f32 v90, v164, v165
	v_cvt_pk_bf16_f32 v91, v94, v95
	v_pk_mul_f32 v[86:87], v[86:87], v[168:169] op_sel_hi:[1,0]
	global_store_dwordx2 v[166:167], v[90:91], off offset:256
	v_pk_fma_f32 v[90:91], v[134:135], v[86:87], v[10:11]
	v_pk_mul_f32 v[86:87], v[88:89], v[168:169] op_sel_hi:[1,0]
	v_pk_mul_f32 v[78:79], v[78:79], v[168:169] op_sel_hi:[1,0]
	v_pk_fma_f32 v[92:93], v[136:137], v[86:87], v[12:13]
	v_pk_mul_f32 v[70:71], v[70:71], v[168:169] op_sel_hi:[1,0]
	v_cvt_pk_bf16_f32 v86, v90, v91
	v_cvt_pk_bf16_f32 v87, v92, v93
	v_pk_fma_f32 v[96:97], v[138:139], v[78:79], v[14:15]
	v_pk_mul_f32 v[78:79], v[80:81], v[168:169] op_sel_hi:[1,0]
	v_pk_fma_f32 v[80:81], v[142:143], v[70:71], v[18:19]
	v_pk_mul_f32 v[70:71], v[72:73], v[168:169] op_sel_hi:[1,0]
	global_store_dwordx2 v[166:167], v[86:87], off offset:512
	v_pk_fma_f32 v[86:87], v[144:145], v[70:71], v[20:21]
	v_cvt_pk_bf16_f32 v70, v80, v81
	v_cvt_pk_bf16_f32 v71, v86, v87
	v_pk_fma_f32 v[88:89], v[140:141], v[78:79], v[16:17]
	global_store_dwordx2 v[166:167], v[70:71], off offset:1024
	v_pk_mul_f32 v[70:71], v[82:83], v[168:169] op_sel_hi:[1,0]
	v_cvt_pk_bf16_f32 v78, v96, v97
	v_cvt_pk_bf16_f32 v79, v88, v89
	v_pk_fma_f32 v[82:83], v[146:147], v[70:71], v[22:23]
	v_pk_mul_f32 v[70:71], v[84:85], v[168:169] op_sel_hi:[1,0]
	global_store_dwordx2 v[166:167], v[78:79], off offset:768
	v_pk_fma_f32 v[78:79], v[148:149], v[70:71], v[24:25]
	v_cvt_pk_bf16_f32 v70, v82, v83
	v_cvt_pk_bf16_f32 v71, v78, v79
	global_store_dwordx2 v[166:167], v[70:71], off offset:1280
	v_pk_mul_f32 v[70:71], v[74:75], v[168:169] op_sel_hi:[1,0]
	v_pk_mul_f32 v[72:73], v[76:77], v[168:169] op_sel_hi:[1,0]
	v_pk_fma_f32 v[70:71], v[150:151], v[70:71], v[26:27]
	v_pk_fma_f32 v[72:73], v[152:153], v[72:73], v[28:29]
	v_cvt_pk_bf16_f32 v74, v70, v71
	v_cvt_pk_bf16_f32 v75, v72, v73
	global_store_dwordx2 v[166:167], v[74:75], off offset:1536
	ds_read_b128 v[74:77], v102 offset:9216
	ds_read_b128 v[188:191], v102 offset:9728
	v_mov_b32_e32 v204, v91
	v_mov_b32_e32 v205, v97
	v_pk_mul_f32 v[170:171], v[66:67], v[168:169] op_sel_hi:[1,0]
	v_pk_mul_f32 v[66:67], v[68:69], v[168:169] op_sel_hi:[1,0]
	s_waitcnt lgkmcnt(0)
; #define HSUM(v) do { v += __shfl_xor(v, 16, 64); v += __shfl_xor(v, 8, 64); v += __shfl_xor(v, 4, 64); v += __shfl_xor(v, 2, 64); v += __shfl_xor(v, 1, 64); } while (0)
; DI void phase5(const Params& p, char* lds0) {
;     ...
; #pragma unroll
;       for (int n = 0; n < 4; ++n) {
;         float a = 0.f;
; #pragma unroll
;         for (int j = 0; j < 8; ++j) {
;           float4 wv = *(const float4*)(wg + n * 1024 + j * 128 + l32 * 4);
;           a += hv[j * 4 + 0] * wv.x + hv[j * 4 + 1] * wv.y + hv[j * 4 + 2] * wv.z + hv[j * 4 + 3] * wv.w;
;         }
;         HSUM(a);
;         lg[n] = a + p.b_rg[n];
	v_mov_b32_e32 v85, v188
	v_mov_b32_e32 v188, v75
	v_mov_b32_e32 v84, v74
	v_mov_b32_e32 v68, v90
	v_mov_b32_e32 v69, v96
	v_pk_mul_f32 v[74:75], v[204:205], v[188:189]
	v_mov_b32_e32 v206, v92
	v_pk_fma_f32 v[74:75], v[68:69], v[84:85], v[74:75]
	v_mov_b32_e32 v84, v76
	v_mov_b32_e32 v85, v190
	v_mov_b32_e32 v207, v88
	v_pk_fma_f32 v[84:85], v[206:207], v[84:85], v[74:75]
	v_mov_b32_e32 v190, v77
	ds_read_b128 v[74:77], v102 offset:10240
	ds_read_b128 v[192:195], v102 offset:10752
	v_mov_b32_e32 v208, v93
	v_mov_b32_e32 v209, v89
	v_pk_fma_f32 v[168:169], v[208:209], v[190:191], v[84:85]
	v_mov_b32_e32 v212, v81
	s_waitcnt lgkmcnt(0)
	v_mov_b32_e32 v85, v192
	v_mov_b32_e32 v192, v75
	v_mov_b32_e32 v213, v83
	v_mov_b32_e32 v84, v74
	v_mov_b32_e32 v210, v80
	v_mov_b32_e32 v211, v82
	v_pk_mul_f32 v[74:75], v[212:213], v[192:193]
	v_mov_b32_e32 v188, v76
	v_pk_fma_f32 v[84:85], v[210:211], v[84:85], v[74:75]
	v_mov_b32_e32 v189, v194
	v_mov_b32_e32 v74, v86
	v_mov_b32_e32 v75, v78
	v_pk_fma_f32 v[84:85], v[74:75], v[188:189], v[84:85]
	ds_read_b128 v[188:191], v102 offset:8192
	ds_read_b128 v[196:199], v102 offset:12288
	v_mov_b32_e32 v194, v77
	v_mov_b32_e32 v76, v87
	v_mov_b32_e32 v77, v79
	v_pk_fma_f32 v[84:85], v[76:77], v[194:195], v[84:85]
	ds_read_b128 v[192:195], v102 offset:8704
	ds_read_b128 v[200:203], v102 offset:12800
	s_waitcnt lgkmcnt(2)
	v_pk_mov_b32 v[214:215], v[188:189], v[196:197] op_sel:[1,0]
	v_mov_b32_e32 v189, v197
	v_pk_mul_f32 v[188:189], v[188:189], v[160:161]
	v_mov_b32_e32 v196, v190
	v_pk_fma_f32 v[188:189], v[214:215], v[160:161], v[188:189] op_sel:[0,1,0] op_sel_hi:[1,0,1]
	v_mov_b32_e32 v197, v198
	v_pk_fma_f32 v[188:189], v[162:163], v[196:197], v[188:189] op_sel_hi:[0,1,1]
	v_mov_b32_e32 v198, v191
	v_pk_fma_f32 v[188:189], v[162:163], v[198:199], v[188:189] op_sel:[1,0,0]
	s_waitcnt vmcnt(7)
	v_pk_fma_f32 v[66:67], v[156:157], v[66:67], v[32:33]
	v_pk_add_f32 v[214:215], v[188:189], 0 op_sel_hi:[1,0]
	s_waitcnt lgkmcnt(0)
	v_pk_mov_b32 v[188:189], v[192:193], v[200:201] op_sel:[1,0]
	v_mov_b32_e32 v193, v201
	v_pk_mul_f32 v[190:191], v[164:165], v[192:193]
	v_cvt_pk_bf16_f32 v173, v66, v67
	v_pk_fma_f32 v[188:189], v[164:165], v[188:189], v[190:191] op_sel:[1,0,0] op_sel_hi:[0,1,1]
	v_mov_b32_e32 v190, v194
	v_mov_b32_e32 v191, v202
	v_pk_fma_f32 v[192:193], v[94:95], v[190:191], v[188:189] op_sel_hi:[0,1,1]
	ds_read_b128 v[188:191], v102 offset:13312
	ds_read_b128 v[196:199], v102 offset:13824
	v_mov_b32_e32 v202, v195
	v_pk_fma_f32 v[192:193], v[94:95], v[202:203], v[192:193] op_sel:[1,0,0]
	s_nop 0
	v_pk_add_f32 v[214:215], v[214:215], v[192:193]
	s_waitcnt lgkmcnt(0)
	v_mov_b32_e32 v193, v196
	v_mov_b32_e32 v196, v189
	v_mov_b32_e32 v192, v188
	v_pk_mul_f32 v[188:189], v[204:205], v[196:197]
	v_mov_b32_e32 v196, v190
	v_pk_fma_f32 v[188:189], v[68:69], v[192:193], v[188:189]
	ds_read_b128 v[192:195], v102 offset:14336
	ds_read_b128 v[200:203], v102 offset:14848
	v_mov_b32_e32 v197, v198
	v_pk_fma_f32 v[188:189], v[206:207], v[196:197], v[188:189]
	v_mov_b32_e32 v198, v191
	v_pk_fma_f32 v[216:217], v[208:209], v[198:199], v[188:189]
	s_waitcnt lgkmcnt(0)
	v_mov_b32_e32 v189, v200
	v_mov_b32_e32 v200, v193
	v_mov_b32_e32 v188, v192
	v_pk_mul_f32 v[190:191], v[212:213], v[200:201]
	v_mov_b32_e32 v196, v194
	v_pk_fma_f32 v[192:193], v[210:211], v[188:189], v[190:191]
	ds_read_b128 v[188:191], v102 offset:16384
	v_mov_b32_e32 v197, v202
	v_pk_fma_f32 v[192:193], v[74:75], v[196:197], v[192:193]
	v_mov_b32_e32 v202, v195
	v_pk_fma_f32 v[218:219], v[76:77], v[202:203], v[192:193]
	ds_read_b128 v[192:195], v102 offset:16896
	s_waitcnt lgkmcnt(1)
	v_mul_f32_e32 v172, v161, v189
	v_fmac_f32_e32 v172, v160, v188
	v_fmac_f32_e32 v172, v162, v190
	v_fmac_f32_e32 v172, v163, v191
	ds_read_b128 v[188:191], v102 offset:17408
	ds_read_b128 v[196:199], v102 offset:17920
	s_waitcnt lgkmcnt(2)
	v_mul_f32_e32 v193, v165, v193
	v_fmac_f32_e32 v193, v164, v192
	v_fmac_f32_e32 v193, v94, v194
	v_add_f32_e32 v172, 0, v172
	v_fmac_f32_e32 v193, v95, v195
	v_add_f32_e32 v172, v172, v193
	s_waitcnt lgkmcnt(0)
	v_mov_b32_e32 v193, v196
	v_mov_b32_e32 v196, v189
	v_mov_b32_e32 v192, v188
	v_pk_mul_f32 v[188:189], v[204:205], v[196:197]
	s_nop 0
	v_pk_fma_f32 v[188:189], v[68:69], v[192:193], v[188:189]
	v_mov_b32_e32 v192, v190
	v_mov_b32_e32 v193, v198
	v_pk_fma_f32 v[196:197], v[206:207], v[192:193], v[188:189]
	v_mov_b32_e32 v198, v191
	ds_read_b128 v[188:191], v102 offset:18432
	ds_read_b128 v[192:195], v102 offset:18944
	v_pk_fma_f32 v[196:197], v[208:209], v[198:199], v[196:197]
	s_nop 0
	v_add_f32_e32 v172, v172, v196
	v_add_f32_e32 v172, v172, v197
	s_waitcnt lgkmcnt(0)
	v_mov_b32_e32 v197, v192
	v_mov_b32_e32 v192, v189
	v_mov_b32_e32 v196, v188
	v_pk_mul_f32 v[188:189], v[212:213], v[192:193]
	v_mov_b32_e32 v192, v190
	v_pk_fma_f32 v[188:189], v[210:211], v[196:197], v[188:189]
	v_mov_b32_e32 v193, v194
	v_pk_fma_f32 v[192:193], v[74:75], v[192:193], v[188:189]
	v_mov_b32_e32 v194, v191
	ds_read_b128 v[188:191], v102 offset:20480
	v_pk_fma_f32 v[192:193], v[76:77], v[194:195], v[192:193]
	s_nop 0
	v_add_f32_e32 v172, v172, v192
	v_add_f32_e32 v220, v172, v193
	ds_read_b128 v[192:195], v102 offset:20992
	s_waitcnt lgkmcnt(1)
	v_mul_f32_e32 v172, v161, v189
	v_fmac_f32_e32 v172, v160, v188
	v_fmac_f32_e32 v172, v162, v190
	v_fmac_f32_e32 v172, v163, v191
	ds_read_b128 v[188:191], v102 offset:21504
	ds_read_b128 v[196:199], v102 offset:22016
	s_waitcnt lgkmcnt(2)
	v_mul_f32_e32 v193, v165, v193
	v_fmac_f32_e32 v193, v164, v192
	v_fmac_f32_e32 v193, v94, v194
	v_add_f32_e32 v172, 0, v172
	v_fmac_f32_e32 v193, v95, v195
	v_add_f32_e32 v172, v172, v193
	s_waitcnt lgkmcnt(0)
; #define HSUM(v) do { v += __shfl_xor(v, 16, 64); v += __shfl_xor(v, 8, 64); v += __shfl_xor(v, 4, 64); v += __shfl_xor(v, 2, 64); v += __shfl_xor(v, 1, 64); } while (0)
; DI void phase5(const Params& p, char* lds0) {
;     ...
;         *(u32x2*)(H + (size_t)t * D + c) = o;
;     ...
; #pragma unroll
;       for (int n = 0; n < 4; ++n) {
;         float a = 0.f;
; #pragma unroll
;         for (int j = 0; j < 8; ++j) {
;           float4 wv = *(const float4*)(wg + n * 1024 + j * 128 + l32 * 4);
;           a += hv[j * 4 + 0] * wv.x + hv[j * 4 + 1] * wv.y + hv[j * 4 + 2] * wv.z + hv[j * 4 + 3] * wv.w;
;         }
;         HSUM(a);
;         lg[n] = a + p.b_rg[n];
	v_mov_b32_e32 v193, v196
	v_mov_b32_e32 v196, v189
	v_mov_b32_e32 v192, v188
	v_pk_mul_f32 v[188:189], v[204:205], v[196:197]
	s_nop 0
	v_pk_fma_f32 v[68:69], v[68:69], v[192:193], v[188:189]
	v_mov_b32_e32 v188, v190
	v_mov_b32_e32 v189, v198
	v_pk_fma_f32 v[68:69], v[206:207], v[188:189], v[68:69]
	v_mov_b32_e32 v198, v191
	ds_read_b128 v[188:191], v102 offset:22528
	ds_read_b128 v[192:195], v102 offset:23040
	v_pk_fma_f32 v[68:69], v[208:209], v[198:199], v[68:69]
	ds_read_b128 v[196:199], v102 offset:11264
	ds_read_b128 v[200:203], v102 offset:11776
	v_add_f32_e32 v68, v172, v68
	v_add_f32_e32 v221, v68, v69
	s_waitcnt lgkmcnt(2)
	v_mov_b32_e32 v69, v192
	v_mov_b32_e32 v192, v189
	v_mov_b32_e32 v68, v188
	v_pk_mul_f32 v[188:189], v[212:213], v[192:193]
	s_waitcnt lgkmcnt(0)
	v_mov_b32_e32 v204, v198
	v_pk_fma_f32 v[188:189], v[210:211], v[68:69], v[188:189]
	v_pk_fma_f32 v[68:69], v[154:155], v[170:171], v[30:31]
	v_mov_b32_e32 v205, v202
	v_cvt_pk_bf16_f32 v172, v68, v69
	global_store_dwordx2 v[166:167], v[172:173], off offset:1792
	v_mov_b32_e32 v166, v196
	v_mov_b32_e32 v167, v200
	v_mov_b32_e32 v200, v197
	v_mov_b32_e32 v202, v199
	ds_read_b128 v[170:173], v102 offset:15360
	ds_read_b128 v[196:199], v102 offset:15872
	v_mov_b32_e32 v212, v71
	v_mov_b32_e32 v213, v69
	v_mov_b32_e32 v210, v70
	v_mov_b32_e32 v211, v68
	v_pk_mul_f32 v[200:201], v[212:213], v[200:201]
	v_mov_b32_e32 v206, v72
	v_mov_b32_e32 v207, v66
	v_pk_fma_f32 v[166:167], v[210:211], v[166:167], v[200:201]
	v_mov_b32_e32 v208, v73
	v_mov_b32_e32 v209, v67
	v_pk_fma_f32 v[166:167], v[206:207], v[204:205], v[166:167]
	v_mov_b32_e32 v192, v190
	v_pk_fma_f32 v[200:201], v[208:209], v[202:203], v[166:167]
	s_waitcnt lgkmcnt(0)
	v_mov_b32_e32 v167, v196
	v_mov_b32_e32 v196, v171
	v_mov_b32_e32 v166, v170
	v_mov_b32_e32 v170, v172
	v_mov_b32_e32 v171, v198
	v_mov_b32_e32 v198, v173
	v_pk_mul_f32 v[172:173], v[212:213], v[196:197]
	v_mov_b32_e32 v196, v84
	v_pk_fma_f32 v[166:167], v[210:211], v[166:167], v[172:173]
	v_mov_b32_e32 v197, v218
	v_pk_fma_f32 v[166:167], v[206:207], v[170:171], v[166:167]
	v_mov_b32_e32 v218, v85
	v_pk_fma_f32 v[170:171], v[208:209], v[198:199], v[166:167]
	v_mov_b32_e32 v166, v168
	v_mov_b32_e32 v167, v216
	v_pk_add_f32 v[166:167], v[214:215], v[166:167]
	v_mov_b32_e32 v216, v169
	v_pk_add_f32 v[172:173], v[166:167], v[216:217]
	global_load_dwordx4 v[166:169], v101, s[28:29]
	v_pk_add_f32 v[172:173], v[172:173], v[196:197]
	v_mov_b32_e32 v193, v194
	v_pk_add_f32 v[84:85], v[172:173], v[218:219]
	v_mov_b32_e32 v172, v200
	v_mov_b32_e32 v173, v170
	v_pk_add_f32 v[84:85], v[84:85], v[172:173]
	v_mov_b32_e32 v170, v201
	v_pk_add_f32 v[84:85], v[84:85], v[170:171]
	ds_bpermute_b32 v170, v176, v84
	ds_bpermute_b32 v171, v176, v85
	v_pk_fma_f32 v[74:75], v[74:75], v[192:193], v[188:189]
	v_mov_b32_e32 v194, v191
	v_pk_fma_f32 v[74:75], v[76:77], v[194:195], v[74:75]
	s_waitcnt lgkmcnt(0)
	v_pk_add_f32 v[84:85], v[84:85], v[170:171]
	v_add_f32_e32 v74, v221, v74
	v_add_f32_e32 v192, v74, v75
	ds_read_b128 v[74:77], v102 offset:19456
	ds_read_b128 v[170:173], v102 offset:19968
	ds_bpermute_b32 v188, v177, v84
	ds_bpermute_b32 v189, v177, v85
	s_waitcnt lgkmcnt(2)
	v_mov_b32_e32 v190, v74
	v_mov_b32_e32 v191, v170
	v_mov_b32_e32 v170, v75
	v_mov_b32_e32 v74, v76
	v_mov_b32_e32 v75, v172
	v_mov_b32_e32 v172, v77
	v_pk_mul_f32 v[76:77], v[212:213], v[170:171]
	s_waitcnt lgkmcnt(0)
	v_pk_add_f32 v[84:85], v[84:85], v[188:189]
	v_pk_fma_f32 v[76:77], v[210:211], v[190:191], v[76:77]
	ds_bpermute_b32 v188, v178, v84
	v_pk_fma_f32 v[74:75], v[206:207], v[74:75], v[76:77]
	ds_bpermute_b32 v189, v178, v85
	v_pk_fma_f32 v[190:191], v[208:209], v[172:173], v[74:75]
	ds_read_b128 v[74:77], v102 offset:23552
	ds_read_b128 v[170:173], v102 offset:24064
	v_add_f32_e32 v190, v220, v190
	v_add_f32_e32 v193, v190, v191
	ds_bpermute_b32 v194, v176, v193
	s_waitcnt lgkmcnt(1)
	v_mov_b32_e32 v190, v74
	v_mov_b32_e32 v191, v170
	v_mov_b32_e32 v170, v75
	v_mov_b32_e32 v74, v76
	v_mov_b32_e32 v75, v172
	v_mov_b32_e32 v172, v77
	v_pk_mul_f32 v[76:77], v[212:213], v[170:171]
	s_nop 0
	v_pk_fma_f32 v[76:77], v[210:211], v[190:191], v[76:77]
	s_nop 0
	v_pk_fma_f32 v[74:75], v[206:207], v[74:75], v[76:77]
	s_nop 0
	v_pk_fma_f32 v[74:75], v[208:209], v[172:173], v[74:75]
	s_nop 0
	v_add_f32_e32 v74, v192, v74
	v_add_f32_e32 v76, v74, v75
	ds_bpermute_b32 v77, v176, v76
	v_pk_add_f32 v[74:75], v[84:85], v[188:189]
	s_waitcnt lgkmcnt(1)
	v_add_f32_e32 v84, v193, v194
	ds_bpermute_b32 v85, v177, v84
	s_waitcnt lgkmcnt(1)
	v_add_f32_e32 v170, v76, v77
	ds_bpermute_b32 v171, v177, v170
	ds_bpermute_b32 v76, v179, v74
	s_waitcnt lgkmcnt(2)
	v_add_f32_e32 v84, v84, v85
	ds_bpermute_b32 v85, v178, v84
	ds_bpermute_b32 v77, v179, v75
	s_waitcnt lgkmcnt(3)
	v_add_f32_e32 v170, v170, v171
	ds_bpermute_b32 v171, v178, v170
	s_waitcnt lgkmcnt(2)
	v_add_f32_e32 v84, v84, v85
	ds_bpermute_b32 v85, v179, v84
	s_waitcnt lgkmcnt(1)
	v_pk_add_f32 v[74:75], v[74:75], v[76:77]
	v_add_f32_e32 v170, v170, v171
	ds_bpermute_b32 v171, v179, v170
	ds_bpermute_b32 v76, v180, v74
	ds_bpermute_b32 v77, v180, v75
	s_waitcnt lgkmcnt(3)
	v_add_f32_e32 v84, v84, v85
	ds_bpermute_b32 v85, v180, v84
	s_waitcnt lgkmcnt(3)
	v_add_f32_e32 v170, v170, v171
	ds_bpermute_b32 v171, v180, v170
	s_waitcnt lgkmcnt(1)
	v_pk_add_f32 v[74:75], v[74:75], v[76:77]
	v_add_f32_e32 v76, v84, v85
	s_waitcnt vmcnt(0)
	v_pk_add_f32 v[74:75], v[166:167], v[74:75]
	v_add_f32_e32 v168, v168, v76
	s_waitcnt lgkmcnt(0)
; #define HSUM(v) do { v += __shfl_xor(v, 16, 64); v += __shfl_xor(v, 8, 64); v += __shfl_xor(v, 4, 64); v += __shfl_xor(v, 2, 64); v += __shfl_xor(v, 1, 64); } while (0)
; DI void phase5(const Params& p, char* lds0) {
;     ...
;       int g = 0; float gm = lg[0];
; #pragma unroll
;       for (int n = 1; n < 4; ++n) if (lg[n] > gm) { gm = lg[n]; g = n; }
;       float den = 0.f;
; #pragma unroll
;       for (int n = 0; n < 4; ++n) den += __expf(lg[n] - gm);
;       const float pgrp = 1.f / den;
;       float le[8];
; #pragma unroll
;       for (int e = 0; e < 8; ++e) {
;         const float* wr = wg + (4 + g * 8 + e) * 1024;
;         float a = 0.f;
; #pragma unroll
;         for (int j = 0; j < 8; ++j) {
;           float4 wv = *(const float4*)(wr + j * 128 + l32 * 4);
;           a += hv[j * 4 + 0] * wv.x + hv[j * 4 + 1] * wv.y + hv[j * 4 + 2] * wv.z + hv[j * 4 + 3] * wv.w;
;         }
;         HSUM(a);
;         le[e] = a + p.b_re[g * 8 + e];
;       }
	v_add_f32_e32 v76, v170, v171
	v_cmp_gt_f32_e32 vcc, v75, v74
	v_add_f32_e32 v167, v169, v76
	s_nop 0
	v_cndmask_b32_e32 v76, v74, v75, vcc
	v_cmp_gt_f32_e64 s[6:7], v168, v76
	s_nop 1
	v_cndmask_b32_e64 v169, v76, v168, s[6:7]
	v_cndmask_b32_e64 v76, 0, 8, vcc
	v_cndmask_b32_e64 v76, v76, 16, s[6:7]
	v_cmp_gt_f32_e32 vcc, v167, v169
	s_nop 1
	v_cndmask_b32_e64 v166, v76, 24, vcc
	v_lshl_or_b32 v170, v166, 12, v102
	ds_read_b128 v[188:191], v170 offset:26624
	ds_read_b128 v[192:195], v170 offset:27136
	ds_read_b128 v[196:199], v170 offset:24576
	ds_read_b128 v[200:203], v170 offset:28672
	ds_read_b128 v[204:207], v170 offset:27648
	ds_read_b128 v[208:211], v170 offset:28160
	ds_read_b128 v[212:215], v170 offset:25088
	ds_read_b128 v[216:219], v170 offset:29184
	s_waitcnt lgkmcnt(4)
	v_pk_mov_b32 v[76:77], v[196:197], v[200:201] op_sel:[1,0]
	v_mov_b32_e32 v197, v201
	v_pk_mul_f32 v[84:85], v[160:161], v[196:197]
	s_nop 0
	v_pk_fma_f32 v[76:77], v[160:161], v[76:77], v[84:85] op_sel:[1,0,0] op_sel_hi:[0,1,1]
	v_mov_b32_e32 v84, v198
	v_mov_b32_e32 v85, v202
	v_pk_fma_f32 v[76:77], v[162:163], v[84:85], v[76:77] op_sel_hi:[0,1,1]
	v_mov_b32_e32 v202, v199
	v_pk_fma_f32 v[76:77], v[162:163], v[202:203], v[76:77] op_sel:[1,0,0]
	s_waitcnt lgkmcnt(0)
	v_pk_mov_b32 v[84:85], v[212:213], v[216:217] op_sel:[1,0]
	v_mov_b32_e32 v213, v217
	ds_read_b128 v[196:199], v170 offset:26112
	ds_read_b128 v[200:203], v170 offset:25600
	ds_read_b128 v[220:223], v170 offset:29696
	v_pk_mul_f32 v[172:173], v[164:165], v[212:213]
	v_pk_add_f32 v[76:77], v[76:77], 0 op_sel_hi:[1,0]
	v_pk_fma_f32 v[84:85], v[164:165], v[84:85], v[172:173] op_sel:[1,0,0] op_sel_hi:[0,1,1]
	v_mov_b32_e32 v172, v214
	v_mov_b32_e32 v173, v218
	v_pk_fma_f32 v[84:85], v[94:95], v[172:173], v[84:85] op_sel_hi:[0,1,1]
	v_mov_b32_e32 v218, v215
	v_pk_fma_f32 v[84:85], v[94:95], v[218:219], v[84:85] op_sel:[1,0,0]
	ds_read_b128 v[212:215], v170 offset:30208
	v_pk_add_f32 v[76:77], v[76:77], v[84:85]
	s_waitcnt lgkmcnt(1)
	v_pk_mov_b32 v[84:85], v[200:201], v[220:221] op_sel:[1,0]
	v_mov_b32_e32 v201, v221
	v_pk_mul_f32 v[172:173], v[90:91], v[200:201]
	s_nop 0
	v_pk_fma_f32 v[84:85], v[90:91], v[84:85], v[172:173] op_sel:[1,0,0] op_sel_hi:[0,1,1]
	v_mov_b32_e32 v172, v202
	v_mov_b32_e32 v173, v222
	v_pk_fma_f32 v[84:85], v[92:93], v[172:173], v[84:85] op_sel_hi:[0,1,1]
	v_mov_b32_e32 v222, v203
	v_pk_fma_f32 v[84:85], v[92:93], v[222:223], v[84:85] op_sel:[1,0,0]
	ds_read_b128 v[200:203], v170 offset:30720
	v_pk_add_f32 v[76:77], v[76:77], v[84:85]
	s_waitcnt lgkmcnt(1)
	v_pk_mov_b32 v[84:85], v[196:197], v[212:213] op_sel:[1,0]
	v_mov_b32_e32 v197, v213
	v_pk_mul_f32 v[172:173], v[96:97], v[196:197]
	s_nop 0
	v_pk_fma_f32 v[84:85], v[96:97], v[84:85], v[172:173] op_sel:[1,0,0] op_sel_hi:[0,1,1]
	v_mov_b32_e32 v172, v198
	v_mov_b32_e32 v173, v214
	v_pk_fma_f32 v[84:85], v[88:89], v[172:173], v[84:85] op_sel_hi:[0,1,1]
	v_mov_b32_e32 v214, v199
	v_pk_fma_f32 v[84:85], v[88:89], v[214:215], v[84:85] op_sel:[1,0,0]
	ds_read_b128 v[196:199], v170 offset:31232
	v_pk_add_f32 v[76:77], v[76:77], v[84:85]
	s_waitcnt lgkmcnt(1)
	v_pk_mov_b32 v[84:85], v[188:189], v[200:201] op_sel:[1,0]
	v_mov_b32_e32 v189, v201
	v_pk_mul_f32 v[172:173], v[80:81], v[188:189]
	s_nop 0
	v_pk_fma_f32 v[84:85], v[80:81], v[84:85], v[172:173] op_sel:[1,0,0] op_sel_hi:[0,1,1]
	v_mov_b32_e32 v172, v190
	v_mov_b32_e32 v173, v202
	v_pk_fma_f32 v[84:85], v[86:87], v[172:173], v[84:85] op_sel_hi:[0,1,1]
	v_mov_b32_e32 v202, v191
	v_pk_fma_f32 v[84:85], v[86:87], v[202:203], v[84:85] op_sel:[1,0,0]
	ds_read_b128 v[188:191], v170 offset:31744
	v_pk_add_f32 v[76:77], v[76:77], v[84:85]
	v_mov_b32_e32 v84, v193
	s_waitcnt lgkmcnt(1)
	v_mov_b32_e32 v85, v196
	v_pk_mul_f32 v[84:85], v[82:83], v[84:85] op_sel:[1,0] op_sel_hi:[0,1]
	v_mov_b32_e32 v193, v197
	v_pk_fma_f32 v[84:85], v[82:83], v[192:193], v[84:85]
	v_mov_b32_e32 v172, v194
	v_mov_b32_e32 v173, v198
	v_pk_fma_f32 v[84:85], v[78:79], v[172:173], v[84:85] op_sel_hi:[0,1,1]
	v_mov_b32_e32 v198, v195
	v_pk_fma_f32 v[84:85], v[78:79], v[198:199], v[84:85] op_sel:[1,0,0]
	ds_read_b128 v[192:195], v170 offset:32256
	v_pk_add_f32 v[76:77], v[76:77], v[84:85]
	s_waitcnt lgkmcnt(1)
	v_mov_b32_e32 v84, v188
	v_mov_b32_e32 v85, v205
	v_pk_mul_f32 v[84:85], v[70:71], v[84:85]
	v_mov_b32_e32 v205, v189
	v_pk_fma_f32 v[84:85], v[70:71], v[204:205], v[84:85] op_sel:[0,0,1] op_sel_hi:[1,1,0]
	v_mov_b32_e32 v172, v206
	v_mov_b32_e32 v173, v190
	v_pk_fma_f32 v[84:85], v[72:73], v[172:173], v[84:85] op_sel_hi:[0,1,1]
	v_mov_b32_e32 v190, v207
	v_pk_fma_f32 v[84:85], v[72:73], v[190:191], v[84:85] op_sel:[1,0,0]
	ds_read_b128 v[188:191], v170 offset:32768
	v_pk_add_f32 v[76:77], v[76:77], v[84:85]
	s_waitcnt lgkmcnt(1)
	v_pk_mov_b32 v[84:85], v[208:209], v[192:193] op_sel:[1,0]
	v_mov_b32_e32 v209, v193
	v_pk_mul_f32 v[84:85], v[68:69], v[84:85] op_sel:[1,0] op_sel_hi:[0,1]
	v_pk_fma_f32 v[84:85], v[68:69], v[208:209], v[84:85]
	v_mov_b32_e32 v172, v210
	v_mov_b32_e32 v173, v194
	v_pk_fma_f32 v[84:85], v[66:67], v[172:173], v[84:85] op_sel_hi:[0,1,1]
	v_mov_b32_e32 v194, v211
	v_pk_fma_f32 v[84:85], v[66:67], v[194:195], v[84:85] op_sel:[1,0,0]
	ds_read_b128 v[192:195], v170 offset:33280
	s_waitcnt lgkmcnt(1)
	v_mul_f32_e32 v171, v161, v189
	v_fmac_f32_e32 v171, v160, v188
	v_fmac_f32_e32 v171, v162, v190
	v_fmac_f32_e32 v171, v163, v191
	ds_read_b128 v[188:191], v170 offset:33792
	s_waitcnt lgkmcnt(1)
	v_mul_f32_e32 v172, v165, v193
	v_fmac_f32_e32 v172, v164, v192
	v_fmac_f32_e32 v172, v94, v194
	v_add_f32_e32 v171, 0, v171
	v_fmac_f32_e32 v172, v95, v195
	ds_read_b128 v[192:195], v170 offset:34304
	v_add_f32_e32 v171, v171, v172
	s_waitcnt lgkmcnt(1)
; #define HSUM(v) do { v += __shfl_xor(v, 16, 64); v += __shfl_xor(v, 8, 64); v += __shfl_xor(v, 4, 64); v += __shfl_xor(v, 2, 64); v += __shfl_xor(v, 1, 64); } while (0)
; DI void phase5(const Params& p, char* lds0) {
;     ...
;       float lg[4];
; #pragma unroll
;       for (int n = 0; n < 4; ++n) {
;         float a = 0.f;
; #pragma unroll
;         for (int j = 0; j < 8; ++j) {
;           float4 wv = *(const float4*)(wg + n * 1024 + j * 128 + l32 * 4);
;           a += hv[j * 4 + 0] * wv.x + hv[j * 4 + 1] * wv.y + hv[j * 4 + 2] * wv.z + hv[j * 4 + 3] * wv.w;
;         }
;         HSUM(a);
;         lg[n] = a + p.b_rg[n];
;       }
;       int g = 0; float gm = lg[0];
; #pragma unroll
;       for (int n = 1; n < 4; ++n) if (lg[n] > gm) { gm = lg[n]; g = n; }
;       float den = 0.f;
; #pragma unroll
;       for (int n = 0; n < 4; ++n) den += __expf(lg[n] - gm);
;       const float pgrp = 1.f / den;
;       float le[8];
; #pragma unroll
;       for (int e = 0; e < 8; ++e) {
;         const float* wr = wg + (4 + g * 8 + e) * 1024;
;         float a = 0.f;
; #pragma unroll
;         for (int j = 0; j < 8; ++j) {
;           float4 wv = *(const float4*)(wr + j * 128 + l32 * 4);
;           a += hv[j * 4 + 0] * wv.x + hv[j * 4 + 1] * wv.y + hv[j * 4 + 2] * wv.z + hv[j * 4 + 3] * wv.w;
;         }
;         HSUM(a);
;         le[e] = a + p.b_re[g * 8 + e];
;       }
	v_mul_f32_e32 v172, v91, v189
	v_fmac_f32_e32 v172, v90, v188
	v_fmac_f32_e32 v172, v92, v190
	v_fmac_f32_e32 v172, v93, v191
	ds_read_b128 v[188:191], v170 offset:34816
	v_add_f32_e32 v171, v171, v172
	s_waitcnt lgkmcnt(1)
	v_mul_f32_e32 v172, v97, v193
	v_fmac_f32_e32 v172, v96, v192
	v_fmac_f32_e32 v172, v88, v194
	v_fmac_f32_e32 v172, v89, v195
	ds_read_b128 v[192:195], v170 offset:35328
	v_pk_add_f32 v[76:77], v[76:77], v[84:85]
	v_add_f32_e32 v171, v171, v172
	s_waitcnt lgkmcnt(1)
	v_mul_f32_e32 v172, v81, v189
	ds_bpermute_b32 v84, v176, v76
	ds_bpermute_b32 v85, v176, v77
	v_fmac_f32_e32 v172, v80, v188
	v_fmac_f32_e32 v172, v86, v190
	v_fmac_f32_e32 v172, v87, v191
	ds_read_b128 v[188:191], v170 offset:35840
	v_add_f32_e32 v171, v171, v172
	s_waitcnt lgkmcnt(1)
	v_mul_f32_e32 v172, v83, v193
	v_fmac_f32_e32 v172, v82, v192
	v_pk_add_f32 v[76:77], v[76:77], v[84:85]
	v_fmac_f32_e32 v172, v78, v194
	ds_bpermute_b32 v84, v177, v76
	ds_bpermute_b32 v85, v177, v77
	v_fmac_f32_e32 v172, v79, v195
	ds_read_b128 v[192:195], v170 offset:36352
	v_add_f32_e32 v171, v171, v172
	s_waitcnt lgkmcnt(3)
	v_mul_f32_e32 v172, v71, v189
	v_fmac_f32_e32 v172, v70, v188
	v_fmac_f32_e32 v172, v72, v190
	v_fmac_f32_e32 v172, v73, v191
	s_waitcnt lgkmcnt(0)
	v_pk_add_f32 v[76:77], v[76:77], v[84:85]
	v_add_f32_e32 v171, v171, v172
	v_mul_f32_e32 v172, v69, v193
	ds_bpermute_b32 v84, v178, v76
	ds_bpermute_b32 v85, v178, v77
	v_fmac_f32_e32 v172, v68, v192
	v_fmac_f32_e32 v172, v66, v194
	v_fmac_f32_e32 v172, v67, v195
	v_add_f32_e32 v171, v171, v172
	ds_bpermute_b32 v172, v176, v171
	s_waitcnt lgkmcnt(1)
	v_pk_add_f32 v[76:77], v[76:77], v[84:85]
	ds_bpermute_b32 v84, v179, v76
	ds_bpermute_b32 v85, v179, v77
	ds_read_b128 v[188:191], v170 offset:36864
	s_waitcnt lgkmcnt(3)
	v_add_f32_e32 v171, v171, v172
	ds_bpermute_b32 v172, v177, v171
	ds_read_b128 v[192:195], v170 offset:37376
	s_waitcnt lgkmcnt(2)
	v_pk_add_f32 v[76:77], v[76:77], v[84:85]
	v_mul_f32_e32 v84, v161, v189
	v_fmac_f32_e32 v84, v160, v188
	v_fmac_f32_e32 v84, v162, v190
	v_fmac_f32_e32 v84, v163, v191
	ds_read_b128 v[188:191], v170 offset:37888
	s_waitcnt lgkmcnt(1)
	v_add_f32_e32 v85, v171, v172
	v_mul_f32_e32 v171, v165, v193
	v_fmac_f32_e32 v171, v164, v192
	v_fmac_f32_e32 v171, v94, v194
	v_add_f32_e32 v84, 0, v84
	v_fmac_f32_e32 v171, v95, v195
	ds_read_b128 v[192:195], v170 offset:38400
	v_add_f32_e32 v84, v84, v171
	s_waitcnt lgkmcnt(1)
	v_mul_f32_e32 v171, v91, v189
	v_fmac_f32_e32 v171, v90, v188
	v_fmac_f32_e32 v171, v92, v190
	v_fmac_f32_e32 v171, v93, v191
	ds_read_b128 v[188:191], v170 offset:38912
	v_add_f32_e32 v84, v84, v171
	s_waitcnt lgkmcnt(1)
	v_mul_f32_e32 v171, v97, v193
	v_fmac_f32_e32 v171, v96, v192
	v_fmac_f32_e32 v171, v88, v194
	v_fmac_f32_e32 v171, v89, v195
	ds_read_b128 v[192:195], v170 offset:39424
	v_add_f32_e32 v84, v84, v171
	s_waitcnt lgkmcnt(1)
	v_mul_f32_e32 v171, v81, v189
	v_fmac_f32_e32 v171, v80, v188
	v_fmac_f32_e32 v171, v86, v190
	v_fmac_f32_e32 v171, v87, v191
	ds_read_b128 v[188:191], v170 offset:39936
	v_add_f32_e32 v84, v84, v171
	s_waitcnt lgkmcnt(1)
	v_mul_f32_e32 v171, v83, v193
	v_fmac_f32_e32 v171, v82, v192
	v_fmac_f32_e32 v171, v78, v194
	v_fmac_f32_e32 v171, v79, v195
	ds_read_b128 v[192:195], v170 offset:40448
	v_add_f32_e32 v84, v84, v171
	s_waitcnt lgkmcnt(1)
	v_mul_f32_e32 v171, v71, v189
	v_fmac_f32_e32 v171, v70, v188
	v_fmac_f32_e32 v171, v72, v190
	v_fmac_f32_e32 v171, v73, v191
	ds_read_b128 v[188:191], v170 offset:40960
	v_add_f32_e32 v84, v84, v171
	s_waitcnt lgkmcnt(1)
	v_mul_f32_e32 v171, v69, v193
	v_fmac_f32_e32 v171, v68, v192
	v_fmac_f32_e32 v171, v66, v194
	v_fmac_f32_e32 v171, v67, v195
	ds_read_b128 v[192:195], v170 offset:41472
	s_waitcnt lgkmcnt(1)
	v_mul_f32_e32 v172, v161, v189
	v_fmac_f32_e32 v172, v160, v188
	v_fmac_f32_e32 v172, v162, v190
	v_fmac_f32_e32 v172, v163, v191
	ds_read_b128 v[188:191], v170 offset:41984
	s_waitcnt lgkmcnt(1)
	v_mul_f32_e32 v173, v165, v193
	v_fmac_f32_e32 v173, v164, v192
	v_fmac_f32_e32 v173, v94, v194
	v_add_f32_e32 v172, 0, v172
	v_fmac_f32_e32 v173, v95, v195
	ds_read_b128 v[192:195], v170 offset:42496
	v_add_f32_e32 v172, v172, v173
	s_waitcnt lgkmcnt(1)
	v_mul_f32_e32 v173, v91, v189
	v_fmac_f32_e32 v173, v90, v188
	v_fmac_f32_e32 v173, v92, v190
	v_fmac_f32_e32 v173, v93, v191
	ds_read_b128 v[188:191], v170 offset:43008
	v_add_f32_e32 v172, v172, v173
	s_waitcnt lgkmcnt(1)
	v_mul_f32_e32 v173, v97, v193
	v_fmac_f32_e32 v173, v96, v192
	v_fmac_f32_e32 v173, v88, v194
	v_fmac_f32_e32 v173, v89, v195
	ds_read_b128 v[192:195], v170 offset:43520
	v_add_f32_e32 v172, v172, v173
	s_waitcnt lgkmcnt(1)
	v_mul_f32_e32 v173, v81, v189
	v_fmac_f32_e32 v173, v80, v188
	v_fmac_f32_e32 v173, v86, v190
	v_fmac_f32_e32 v173, v87, v191
	ds_read_b128 v[188:191], v170 offset:44032
	v_add_f32_e32 v172, v172, v173
	s_waitcnt lgkmcnt(1)
	v_mul_f32_e32 v173, v83, v193
	v_fmac_f32_e32 v173, v82, v192
	v_fmac_f32_e32 v173, v78, v194
	v_fmac_f32_e32 v173, v79, v195
	ds_read_b128 v[192:195], v170 offset:44544
	v_add_f32_e32 v172, v172, v173
	s_waitcnt lgkmcnt(1)
	v_mul_f32_e32 v173, v71, v189
	v_fmac_f32_e32 v173, v70, v188
	v_fmac_f32_e32 v173, v72, v190
	v_fmac_f32_e32 v173, v73, v191
	v_add_f32_e32 v172, v172, v173
	s_waitcnt lgkmcnt(0)
	v_mul_f32_e32 v173, v69, v193
	v_fmac_f32_e32 v173, v68, v192
	v_fmac_f32_e32 v173, v66, v194
	v_fmac_f32_e32 v173, v67, v195
	v_add_f32_e32 v84, v84, v171
	v_add_f32_e32 v172, v172, v173
	ds_bpermute_b32 v171, v176, v84
	ds_bpermute_b32 v173, v176, v172
	ds_bpermute_b32 v188, v178, v85
	ds_read_b128 v[192:195], v170 offset:45056
	s_waitcnt lgkmcnt(2)
; #define HSUM(v) do { v += __shfl_xor(v, 16, 64); v += __shfl_xor(v, 8, 64); v += __shfl_xor(v, 4, 64); v += __shfl_xor(v, 2, 64); v += __shfl_xor(v, 1, 64); } while (0)
; DI void phase5(const Params& p, char* lds0) {
;     ...
;       float le[8];
; #pragma unroll
;       for (int e = 0; e < 8; ++e) {
;         const float* wr = wg + (4 + g * 8 + e) * 1024;
;         float a = 0.f;
; #pragma unroll
;         for (int j = 0; j < 8; ++j) {
;           float4 wv = *(const float4*)(wr + j * 128 + l32 * 4);
;           a += hv[j * 4 + 0] * wv.x + hv[j * 4 + 1] * wv.y + hv[j * 4 + 2] * wv.z + hv[j * 4 + 3] * wv.w;
;         }
;         HSUM(a);
;         le[e] = a + p.b_re[g * 8 + e];
;       }
	v_add_f32_e32 v171, v84, v171
	v_add_f32_e32 v172, v172, v173
	ds_bpermute_b32 v189, v177, v171
	ds_bpermute_b32 v173, v177, v172
	s_waitcnt lgkmcnt(3)
	v_add_f32_e32 v188, v85, v188
	ds_bpermute_b32 v190, v179, v188
	ds_bpermute_b32 v84, v180, v76
	s_waitcnt lgkmcnt(2)
	v_add_f32_e32 v171, v171, v189
	v_add_f32_e32 v172, v172, v173
	ds_bpermute_b32 v189, v178, v171
	ds_bpermute_b32 v173, v178, v172
	ds_bpermute_b32 v85, v180, v77
	s_waitcnt lgkmcnt(1)
	v_add_f32_e32 v189, v171, v189
	v_add_f32_e32 v171, v188, v190
	v_add_f32_e32 v190, v172, v173
	ds_bpermute_b32 v191, v179, v189
	ds_bpermute_b32 v196, v179, v190
	ds_bpermute_b32 v172, v180, v171
	s_waitcnt lgkmcnt(1)
	v_add_f32_e32 v173, v189, v191
	v_add_f32_e32 v189, v190, v196
	ds_read_b128 v[196:199], v170 offset:45568
	v_mul_f32_e32 v191, v161, v193
	v_fmac_f32_e32 v191, v160, v192
	v_fmac_f32_e32 v191, v162, v194
	v_fmac_f32_e32 v191, v163, v195
	s_waitcnt lgkmcnt(0)
	v_mul_f32_e32 v197, v165, v197
	v_fmac_f32_e32 v197, v164, v196
	ds_read_b128 v[192:195], v170 offset:46080
	v_fmac_f32_e32 v197, v94, v198
	v_add_f32_e32 v191, 0, v191
	v_fmac_f32_e32 v197, v95, v199
	v_add_f32_e32 v191, v191, v197
	ds_read_b128 v[196:199], v170 offset:46592
	s_waitcnt lgkmcnt(1)
	v_mul_f32_e32 v193, v91, v193
	v_fmac_f32_e32 v193, v90, v192
	v_fmac_f32_e32 v193, v92, v194
	v_fmac_f32_e32 v193, v93, v195
	s_waitcnt lgkmcnt(0)
	v_mul_f32_e32 v197, v97, v197
	v_add_f32_e32 v191, v191, v193
	v_fmac_f32_e32 v197, v96, v196
	ds_read_b128 v[192:195], v170 offset:47104
	v_fmac_f32_e32 v197, v88, v198
	v_fmac_f32_e32 v197, v89, v199
	v_add_f32_e32 v191, v191, v197
	ds_read_b128 v[196:199], v170 offset:47616
	s_waitcnt lgkmcnt(1)
	v_mul_f32_e32 v193, v81, v193
	v_fmac_f32_e32 v193, v80, v192
	v_fmac_f32_e32 v193, v86, v194
	v_fmac_f32_e32 v193, v87, v195
	s_waitcnt lgkmcnt(0)
	v_mul_f32_e32 v197, v83, v197
	v_add_f32_e32 v191, v191, v193
	v_fmac_f32_e32 v197, v82, v196
	ds_read_b128 v[192:195], v170 offset:48128
	v_fmac_f32_e32 v197, v78, v198
	v_fmac_f32_e32 v197, v79, v199
	v_add_f32_e32 v191, v191, v197
	ds_read_b128 v[196:199], v170 offset:48640
	s_waitcnt lgkmcnt(1)
	v_mul_f32_e32 v193, v71, v193
	v_fmac_f32_e32 v193, v70, v192
	v_fmac_f32_e32 v193, v72, v194
	v_fmac_f32_e32 v193, v73, v195
	s_waitcnt lgkmcnt(0)
	v_mul_f32_e32 v197, v69, v197
	v_add_f32_e32 v191, v191, v193
	v_fmac_f32_e32 v197, v68, v196
	ds_read_b128 v[192:195], v170 offset:49152
	v_fmac_f32_e32 v197, v66, v198
	v_fmac_f32_e32 v197, v67, v199
	v_add_f32_e32 v191, v191, v197
	ds_read_b128 v[196:199], v170 offset:49664
	s_waitcnt lgkmcnt(1)
	v_mul_f32_e32 v193, v161, v193
	v_fmac_f32_e32 v193, v160, v192
	v_fmac_f32_e32 v193, v162, v194
	v_fmac_f32_e32 v193, v163, v195
	s_waitcnt lgkmcnt(0)
	v_mul_f32_e32 v197, v165, v197
	v_add_f32_e32 v201, 0, v193
	v_fmac_f32_e32 v197, v164, v196
	ds_read_b128 v[192:195], v170 offset:50176
	v_fmac_f32_e32 v197, v94, v198
	v_fmac_f32_e32 v197, v95, v199
	v_add_f32_e32 v201, v201, v197
	ds_read_b128 v[196:199], v170 offset:50688
	s_waitcnt lgkmcnt(1)
	v_mul_f32_e32 v193, v91, v193
	v_fmac_f32_e32 v193, v90, v192
	v_fmac_f32_e32 v193, v92, v194
	v_fmac_f32_e32 v193, v93, v195
	s_waitcnt lgkmcnt(0)
	v_mul_f32_e32 v197, v97, v197
	v_add_f32_e32 v201, v201, v193
	v_fmac_f32_e32 v197, v96, v196
	ds_read_b128 v[192:195], v170 offset:51200
	v_fmac_f32_e32 v197, v88, v198
	v_fmac_f32_e32 v197, v89, v199
	v_add_f32_e32 v201, v201, v197
	ds_read_b128 v[196:199], v170 offset:51712
	s_waitcnt lgkmcnt(1)
	v_mul_f32_e32 v193, v81, v193
	v_fmac_f32_e32 v193, v80, v192
	v_fmac_f32_e32 v193, v86, v194
	v_fmac_f32_e32 v193, v87, v195
	s_waitcnt lgkmcnt(0)
	v_mul_f32_e32 v197, v83, v197
	v_add_f32_e32 v201, v201, v193
	v_fmac_f32_e32 v197, v82, v196
	ds_read_b128 v[192:195], v170 offset:52224
	v_fmac_f32_e32 v197, v78, v198
	v_fmac_f32_e32 v197, v79, v199
	v_add_f32_e32 v201, v201, v197
	ds_read_b128 v[196:199], v170 offset:52736
	s_waitcnt lgkmcnt(1)
	v_mul_f32_e32 v193, v71, v193
	v_fmac_f32_e32 v193, v70, v192
	v_fmac_f32_e32 v193, v72, v194
	v_fmac_f32_e32 v193, v73, v195
	s_waitcnt lgkmcnt(0)
	v_mul_f32_e32 v197, v69, v197
	v_add_f32_e32 v201, v201, v193
	v_fmac_f32_e32 v197, v68, v196
	ds_read_b128 v[192:195], v170 offset:53248
	v_fmac_f32_e32 v197, v66, v198
	v_fmac_f32_e32 v197, v67, v199
	v_add_f32_e32 v201, v201, v197
	ds_read_b128 v[196:199], v170 offset:53760
	s_waitcnt lgkmcnt(1)
	v_mul_f32_e32 v161, v161, v193
	v_fmac_f32_e32 v161, v160, v192
	v_fmac_f32_e32 v161, v162, v194
	v_fmac_f32_e32 v161, v163, v195
	s_waitcnt lgkmcnt(0)
	v_mul_f32_e32 v165, v165, v197
	v_add_f32_e32 v192, 0, v161
	v_fmac_f32_e32 v165, v164, v196
	ds_read_b128 v[160:163], v170 offset:54272
	v_fmac_f32_e32 v165, v94, v198
	v_fmac_f32_e32 v165, v95, v199
	v_add_f32_e32 v94, v192, v165
	ds_read_b128 v[192:195], v170 offset:54784
	s_waitcnt lgkmcnt(1)
	v_mul_f32_e32 v91, v91, v161
	v_fmac_f32_e32 v91, v90, v160
	v_fmac_f32_e32 v91, v92, v162
	v_fmac_f32_e32 v91, v93, v163
	s_waitcnt lgkmcnt(0)
	v_mul_f32_e32 v95, v97, v193
	v_add_f32_e32 v94, v94, v91
	v_fmac_f32_e32 v95, v96, v192
	ds_read_b128 v[90:93], v170 offset:55296
	v_fmac_f32_e32 v95, v88, v194
	v_fmac_f32_e32 v95, v89, v195
	v_add_f32_e32 v88, v94, v95
	ds_read_b128 v[94:97], v170 offset:55808
	s_waitcnt lgkmcnt(1)
	v_mul_f32_e32 v81, v81, v91
	v_fmac_f32_e32 v81, v80, v90
	v_fmac_f32_e32 v81, v86, v92
	v_fmac_f32_e32 v81, v87, v93
	s_waitcnt lgkmcnt(0)
	v_mul_f32_e32 v87, v83, v95
	v_fmac_f32_e32 v87, v82, v94
	v_fmac_f32_e32 v87, v78, v96
	v_add_f32_e32 v86, v88, v81
	ds_read_b128 v[80:83], v170 offset:56320
	v_fmac_f32_e32 v87, v79, v97
	v_add_f32_e32 v78, v86, v87
	ds_read_b128 v[86:89], v170 offset:56832
	ds_bpermute_b32 v200, v176, v191
	s_waitcnt lgkmcnt(1)
; #define HSUM(v) do { v += __shfl_xor(v, 16, 64); v += __shfl_xor(v, 8, 64); v += __shfl_xor(v, 4, 64); v += __shfl_xor(v, 2, 64); v += __shfl_xor(v, 1, 64); } while (0)
; DI void phase5(const Params& p, char* lds0) {
;     ...
;         HSUM(a);
;         lg[n] = a + p.b_rg[n];
;       }
;       int g = 0; float gm = lg[0];
; #pragma unroll
;       for (int n = 1; n < 4; ++n) if (lg[n] > gm) { gm = lg[n]; g = n; }
;       float den = 0.f;
; #pragma unroll
;       for (int n = 0; n < 4; ++n) den += __expf(lg[n] - gm);
;       const float pgrp = 1.f / den;
;       float le[8];
; #pragma unroll
;       for (int e = 0; e < 8; ++e) {
;         const float* wr = wg + (4 + g * 8 + e) * 1024;
;         float a = 0.f;
; #pragma unroll
;         for (int j = 0; j < 8; ++j) {
;           float4 wv = *(const float4*)(wr + j * 128 + l32 * 4);
;           a += hv[j * 4 + 0] * wv.x + hv[j * 4 + 1] * wv.y + hv[j * 4 + 2] * wv.z + hv[j * 4 + 3] * wv.w;
;         }
;         HSUM(a);
;         le[e] = a + p.b_re[g * 8 + e];
;       }
;     ...
;       int i1 = 0; float v1 = le[0];
; #pragma unroll
;       for (int e = 1; e < 8; ++e) if (le[e] > v1) { v1 = le[e]; i1 = e; }
;       int i2 = -1; float v2 = -3.0e38f;
; #pragma unroll
;       for (int e = 0; e < 8; ++e) if (e != i1 && le[e] > v2) { v2 = le[e]; i2 = e; }
;       const float e2 = __expf(v2 - v1);
;       const float w1 = pgrp / (1.f + e2), w2 = pgrp * e2 / (1.f + e2);
;       if (l32 == 0) {
;         const int li0 = (g * 8 + i1) * 2, li1 = (g * 8 + i2) * 2 + 1;
;         const int lp0 = atomicAdd(&hist[li0], 1), lp1 = atomicAdd(&hist[li1], 1);
;         info[tl * 4 + 0] = li0; info[tl * 4 + 1] = li1; info[tl * 4 + 2] = lp0; info[tl * 4 + 3] = lp1;
;         gate[t] = w1; gate[T + t] = w2;
	v_mul_f32_e32 v71, v71, v81
	v_fmac_f32_e32 v71, v70, v80
	v_fmac_f32_e32 v71, v72, v82
	v_mul_f32_e32 v69, v69, v87
	v_fmac_f32_e32 v69, v68, v86
	v_fmac_f32_e32 v71, v73, v83
	v_fmac_f32_e32 v69, v66, v88
	v_add_f32_e32 v70, v78, v71
	v_fmac_f32_e32 v69, v67, v89
	v_add_f32_e32 v66, v70, v69
	ds_bpermute_b32 v202, v176, v201
	ds_bpermute_b32 v67, v176, v66
	s_waitcnt lgkmcnt(2)
	v_add_f32_e32 v68, v191, v200
	ds_bpermute_b32 v69, v177, v68
	ds_bpermute_b32 v188, v180, v173
	s_waitcnt lgkmcnt(2)
	v_add_f32_e32 v70, v201, v202
	v_add_f32_e32 v66, v66, v67
	ds_bpermute_b32 v71, v177, v70
	ds_bpermute_b32 v67, v177, v66
	s_waitcnt lgkmcnt(3)
	v_add_f32_e32 v68, v68, v69
	ds_bpermute_b32 v69, v178, v68
	ds_bpermute_b32 v190, v180, v189
	s_waitcnt lgkmcnt(2)
	v_add_f32_e32 v70, v70, v71
	v_add_f32_e32 v66, v66, v67
	ds_bpermute_b32 v71, v178, v70
	ds_bpermute_b32 v67, v178, v66
	s_waitcnt lgkmcnt(3)
	v_add_f32_e32 v68, v68, v69
	ds_bpermute_b32 v69, v179, v68
	s_waitcnt lgkmcnt(1)
	v_add_f32_e32 v70, v70, v71
	v_add_f32_e32 v72, v66, v67
	ds_bpermute_b32 v71, v179, v70
	ds_bpermute_b32 v73, v179, v72
	s_waitcnt lgkmcnt(2)
	v_add_f32_e32 v66, v68, v69
	ds_bpermute_b32 v67, v180, v66
	s_waitcnt lgkmcnt(1)
	v_add_f32_e32 v68, v70, v71
	v_add_f32_e32 v70, v72, v73
	ds_bpermute_b32 v69, v180, v68
	ds_bpermute_b32 v71, v180, v70
	s_and_saveexec_b64 s[38:39], s[4:5]
	s_cbranch_execz .LBB0_255
	v_lshlrev_b32_e32 v72, 2, v166
	global_load_dwordx4 v[78:81], v72, s[30:31] offset:16
	global_load_dwordx4 v[86:89], v72, s[30:31]
	s_waitcnt lgkmcnt(1)
	v_add_f32_e32 v68, v68, v69
	v_add_f32_e32 v69, v66, v67
	v_cndmask_b32_e32 v66, v169, v167, vcc
	v_sub_f32_e32 v67, v74, v66
	v_sub_f32_e32 v74, v75, v66
	v_mul_f32_e32 v67, 0x3fb8aa3b, v67
	v_sub_f32_e32 v75, v168, v66
	v_mul_f32_e32 v74, 0x3fb8aa3b, v74
	v_exp_f32_e32 v67, v67
	v_sub_f32_e32 v66, v167, v66
	v_mul_f32_e32 v75, 0x3fb8aa3b, v75
	v_exp_f32_e32 v74, v74
	v_mul_f32_e32 v66, 0x3fb8aa3b, v66
	v_exp_f32_e32 v75, v75
	v_exp_f32_e32 v66, v66
	v_add_f32_e32 v67, 0, v67
	v_add_f32_e32 v67, v74, v67
	v_add_f32_e32 v67, v75, v67
	v_add_f32_e32 v74, v66, v67
	v_pk_add_f32 v[66:67], v[76:77], v[84:85]
	v_add_f32_e32 v73, v171, v172
	v_rcp_f32_e32 v74, v74
	v_add_f32_e32 v72, v173, v188
	s_waitcnt lgkmcnt(0)
	v_add_f32_e32 v70, v70, v71
	v_add_f32_e32 v71, v189, v190
	s_waitcnt vmcnt(1)
	v_add_f32_e32 v71, v71, v78
	s_waitcnt vmcnt(0)
	v_pk_add_f32 v[66:67], v[66:67], v[86:87]
	v_add_f32_e32 v73, v73, v88
	v_cmp_gt_f32_e32 vcc, v67, v66
	v_add_f32_e32 v72, v72, v89
	v_add_f32_e32 v69, v69, v79
	v_cndmask_b32_e32 v75, v66, v67, vcc
	v_cmp_gt_f32_e64 s[8:9], v73, v75
	v_cndmask_b32_e64 v76, 0, 1, vcc
	v_add_f32_e32 v68, v68, v80
	v_cndmask_b32_e64 v75, v75, v73, s[8:9]
	v_cmp_gt_f32_e32 vcc, v72, v75
	v_cndmask_b32_e64 v76, v76, 2, s[8:9]
	v_add_f32_e32 v70, v70, v81
	v_cndmask_b32_e32 v75, v75, v72, vcc
	v_cmp_gt_f32_e64 s[8:9], v71, v75
	v_cndmask_b32_e64 v76, v76, 3, vcc
	v_cmp_nlt_f32_e64 s[6:7], s41, v66
	v_cndmask_b32_e64 v75, v75, v71, s[8:9]
	v_cmp_gt_f32_e32 vcc, v69, v75
	v_cndmask_b32_e64 v76, v76, 4, s[8:9]
	s_nop 0
	v_cndmask_b32_e32 v75, v75, v69, vcc
	v_cmp_gt_f32_e64 s[8:9], v68, v75
	v_cndmask_b32_e64 v76, v76, 5, vcc
	s_nop 0
	v_cndmask_b32_e64 v75, v75, v68, s[8:9]
	v_cndmask_b32_e64 v76, v76, 6, s[8:9]
	v_cmp_ngt_f32_e32 vcc, v70, v75
	s_and_b64 s[46:47], s[8:9], vcc
	s_nop 0
	v_cndmask_b32_e32 v76, 7, v76, vcc
	v_cmp_eq_u32_e64 s[18:19], 0, v76
	s_or_b64 s[6:7], s[18:19], s[6:7]
	v_cndmask_b32_e64 v66, v66, v185, s[6:7]
	v_cmp_ne_u32_e64 s[16:17], 1, v76
	v_cmp_gt_f32_e64 s[18:19], v67, v66
	v_cndmask_b32_e64 v77, 0, -1, s[6:7]
	s_and_b64 s[6:7], s[16:17], s[18:19]
	v_cndmask_b32_e64 v66, v66, v67, s[6:7]
	v_cmp_ne_u32_e64 s[14:15], 2, v76
	v_cmp_gt_f32_e64 s[16:17], v73, v66
	v_cndmask_b32_e64 v67, v77, 1, s[6:7]
	s_and_b64 s[6:7], s[14:15], s[16:17]
	v_cndmask_b32_e64 v66, v66, v73, s[6:7]
	v_cmp_ne_u32_e64 s[12:13], 3, v76
	v_cmp_gt_f32_e64 s[14:15], v72, v66
	v_cndmask_b32_e64 v67, v67, 2, s[6:7]
	s_and_b64 s[6:7], s[12:13], s[14:15]
	v_cndmask_b32_e64 v66, v66, v72, s[6:7]
	v_cmp_ne_u32_e64 s[10:11], 4, v76
	v_cmp_gt_f32_e64 s[12:13], v71, v66
	v_cndmask_b32_e64 v67, v67, 3, s[6:7]
	s_and_b64 s[6:7], s[10:11], s[12:13]
	v_cndmask_b32_e64 v66, v66, v71, s[6:7]
	v_cmp_ne_u32_e64 s[8:9], 5, v76
	v_cmp_gt_f32_e64 s[10:11], v69, v66
	s_and_b64 s[8:9], s[8:9], s[10:11]
	v_cndmask_b32_e64 v66, v66, v69, s[8:9]
	v_cmp_ngt_f32_e64 s[10:11], v68, v66
	s_or_b64 s[10:11], s[46:47], s[10:11]
	v_cndmask_b32_e32 v75, v70, v75, vcc
	v_cndmask_b32_e64 v66, v68, v66, s[10:11]
	v_cmp_gt_f32_e64 s[12:13], v70, v66
	s_and_b64 vcc, vcc, s[12:13]
	v_cndmask_b32_e32 v66, v66, v70, vcc
	v_sub_f32_e32 v66, v66, v75
	v_mul_f32_e32 v66, 0x3fb8aa3b, v66
	v_exp_f32_e32 v66, v66
	v_cndmask_b32_e64 v67, v67, 4, s[6:7]
	v_cndmask_b32_e64 v67, v67, 5, s[8:9]
	v_cndmask_b32_e64 v67, 6, v67, s[10:11]
	v_mul_f32_e32 v68, v74, v66
	v_add_f32_e32 v66, 1.0, v66
	v_cndmask_b32_e64 v67, v67, 7, vcc
	v_rcp_f32_e32 v69, v66
	v_or_b32_e32 v75, v76, v166
	v_mul_f32_e32 v70, v68, v69
	v_add_u32_e32 v67, v67, v166
	v_lshl_add_u32 v68, v75, 3, v1
	ds_add_rtn_u32 v68, v68, v183
	v_lshl_add_u32 v69, v67, 3, v1
	ds_add_rtn_u32 v69, v69, v183 offset:4
	v_rcp_f32_e32 v71, v66
	s_nop 0
	v_mul_f32_e32 v71, v74, v71
	v_lshlrev_b32_e32 v66, 1, v75
	v_lshl_or_b32 v67, v67, 1, 1
	s_waitcnt lgkmcnt(0)
	ds_write_b128 v187, v[66:69]
	v_lshl_add_u64 v[66:67], v[158:159], 2, s[22:23]
	global_store_dword v[66:67], v71, off
	v_add_co_u32_e32 v66, vcc, 0x60000, v66
	s_nop 1
	v_addc_co_u32_e32 v67, vcc, 0, v67, vcc
	global_store_dword v[66:67], v70, off
	s_branch .LBB0_255
